# norm phases: context-row split-K partial loads issued in batches instead of one-at-a-time
# speedup vs baseline: 1.0030x; 1.0030x over previous
; __device__ void norm_mod_phase(const float* srcL, const float* srcC, float* cpyL, float* cpyC, const float* g, const float* mod, bf16_t* TN, int nrows, const float* pb, int nsl) {
;     ...
;         const float* sp = lat ? srcL + (size_t)row * 1024 : srcC + (size_t)(row - RL) * 1024;
;         const float* mp = mod + (lat ? (row >> 13) : 4) * 9216;
;         f32x4 v[4]; float ss = 0.f;
; #pragma unroll
;         for (int j = 0; j < 4; ++j) v[j] = *(const f32x4*)(sp + 256 * j + 4 * lane);
;         if (!lat && nsl > 0) {
;             for (int sl = 0; sl < nsl; ++sl) { const float* pp = pb + ((size_t)sl * 1024 + (row - RL)) * 1024;
; #pragma unroll
;                 for (int j = 0; j < 4; ++j) v[j] += *(const f32x4*)(pp + 256 * j + 4 * lane); }
;             float* wp = (float*)sp;
; #pragma unroll
;             for (int j = 0; j < 4; ++j) *(f32x4*)(wp + 256 * j + 4 * lane) = v[j];
;         }
.LBB0_29:
	v_add_u32_e32 v38, 0xffff8000, v18
	v_cmp_lt_i32_e32 vcc, s57, v18
	v_mov_b32_e32 v39, v0
	s_nop 0
	v_cndmask_b32_e64 v3, v19, 0, vcc
	v_cndmask_b32_e32 v2, v18, v38, vcc
	v_cndmask_b32_e32 v5, v1, v42, vcc
	v_cndmask_b32_e32 v4, v43, v44, vcc
	v_lshlrev_b64 v[2:3], 12, v[2:3]
	v_lshl_add_u64 v[2:3], v[4:5], 0, v[2:3]
	v_lshl_add_u64 v[36:37], v[2:3], 0, v[28:29]
	global_load_dwordx4 v[14:17], v[36:37], off
	global_load_dwordx4 v[10:13], v[36:37], off offset:1024
	global_load_dwordx4 v[6:9], v[36:37], off offset:2048
	global_load_dwordx4 v[2:5], v[36:37], off offset:3072
	s_and_saveexec_b64 s[2:3], vcc
	s_cbranch_execz .LBB0_28
	v_lshlrev_b64 v[38:39], 12, v[38:39]
	v_lshl_add_u64 v[46:47], v[20:21], 0, v[38:39]
	global_load_dwordx4 v[60:63], v[46:47], off
	global_load_dwordx4 v[64:67], v[46:47], off offset:1024
	global_load_dwordx4 v[68:71], v[46:47], off offset:2048
	global_load_dwordx4 v[72:75], v[46:47], off offset:3072
	s_mov_b32 s1, 0x400000
	v_add_co_u32_e32 v48, vcc, s1, v46
	s_nop 1
	v_addc_co_u32_e32 v49, vcc, 0, v47, vcc
	global_load_dwordx4 v[76:79], v[48:49], off
	global_load_dwordx4 v[80:83], v[48:49], off offset:1024
	global_load_dwordx4 v[84:87], v[48:49], off offset:2048
	global_load_dwordx4 v[88:91], v[48:49], off offset:3072
	s_mov_b32 s1, 0x800000
	v_add_co_u32_e32 v48, vcc, s1, v46
	s_nop 1
	v_addc_co_u32_e32 v49, vcc, 0, v47, vcc
	global_load_dwordx4 v[92:95], v[48:49], off
	global_load_dwordx4 v[96:99], v[48:49], off offset:1024
	global_load_dwordx4 v[100:103], v[48:49], off offset:2048
	global_load_dwordx4 v[104:107], v[48:49], off offset:3072
	s_mov_b32 s1, 0xc00000
	v_add_co_u32_e32 v48, vcc, s1, v46
	s_nop 1
	v_addc_co_u32_e32 v49, vcc, 0, v47, vcc
	global_load_dwordx4 v[108:111], v[48:49], off
	global_load_dwordx4 v[112:115], v[48:49], off offset:1024
	global_load_dwordx4 v[116:119], v[48:49], off offset:2048
	global_load_dwordx4 v[120:123], v[48:49], off offset:3072
	s_waitcnt vmcnt(15)
	v_pk_add_f32 v[14:15], v[14:15], v[60:61]
	v_pk_add_f32 v[16:17], v[16:17], v[62:63]
	s_waitcnt vmcnt(14)
	v_pk_add_f32 v[10:11], v[10:11], v[64:65]
	v_pk_add_f32 v[12:13], v[12:13], v[66:67]
	s_waitcnt vmcnt(13)
	v_pk_add_f32 v[6:7], v[6:7], v[68:69]
	v_pk_add_f32 v[8:9], v[8:9], v[70:71]
	s_waitcnt vmcnt(12)
	v_pk_add_f32 v[2:3], v[2:3], v[72:73]
	v_pk_add_f32 v[4:5], v[4:5], v[74:75]
	s_waitcnt vmcnt(11)
	v_pk_add_f32 v[14:15], v[14:15], v[76:77]
	v_pk_add_f32 v[16:17], v[16:17], v[78:79]
	s_waitcnt vmcnt(10)
	v_pk_add_f32 v[10:11], v[10:11], v[80:81]
	v_pk_add_f32 v[12:13], v[12:13], v[82:83]
	s_waitcnt vmcnt(9)
	v_pk_add_f32 v[6:7], v[6:7], v[84:85]
	v_pk_add_f32 v[8:9], v[8:9], v[86:87]
	s_waitcnt vmcnt(8)
	v_pk_add_f32 v[2:3], v[2:3], v[88:89]
	v_pk_add_f32 v[4:5], v[4:5], v[90:91]
	s_waitcnt vmcnt(7)
	v_pk_add_f32 v[14:15], v[14:15], v[92:93]
	v_pk_add_f32 v[16:17], v[16:17], v[94:95]
	s_waitcnt vmcnt(6)
	v_pk_add_f32 v[10:11], v[10:11], v[96:97]
	v_pk_add_f32 v[12:13], v[12:13], v[98:99]
	s_waitcnt vmcnt(5)
	v_pk_add_f32 v[6:7], v[6:7], v[100:101]
	v_pk_add_f32 v[8:9], v[8:9], v[102:103]
	s_waitcnt vmcnt(4)
	v_pk_add_f32 v[2:3], v[2:3], v[104:105]
	v_pk_add_f32 v[4:5], v[4:5], v[106:107]
	s_waitcnt vmcnt(3)
	v_pk_add_f32 v[14:15], v[14:15], v[108:109]
	v_pk_add_f32 v[16:17], v[16:17], v[110:111]
	s_waitcnt vmcnt(2)
	v_pk_add_f32 v[10:11], v[10:11], v[112:113]
	v_pk_add_f32 v[12:13], v[12:13], v[114:115]
	s_waitcnt vmcnt(1)
	v_pk_add_f32 v[6:7], v[6:7], v[116:117]
	v_pk_add_f32 v[8:9], v[8:9], v[118:119]
	s_waitcnt vmcnt(0)
	v_pk_add_f32 v[2:3], v[2:3], v[120:121]
	v_pk_add_f32 v[4:5], v[4:5], v[122:123]
	global_store_dwordx4 v[36:37], v[14:17], off
	global_store_dwordx4 v[36:37], v[10:13], off offset:1024
	global_store_dwordx4 v[36:37], v[6:9], off offset:2048
	global_store_dwordx4 v[36:37], v[2:5], off offset:3072
	s_branch .LBB0_28

; __device__ void norm_mod_phase(const float* srcL, const float* srcC, float* cpyL, float* cpyC, const float* g, const float* mod, bf16_t* TN, int nrows, const float* pb, int nsl) {
;     ...
;         const float* sp = lat ? srcL + (size_t)row * 1024 : srcC + (size_t)(row - RL) * 1024;
;         const float* mp = mod + (lat ? (row >> 13) : 4) * 9216;
;         f32x4 v[4]; float ss = 0.f;
; #pragma unroll
;         for (int j = 0; j < 4; ++j) v[j] = *(const f32x4*)(sp + 256 * j + 4 * lane);
;         if (!lat && nsl > 0) {
;             for (int sl = 0; sl < nsl; ++sl) { const float* pp = pb + ((size_t)sl * 1024 + (row - RL)) * 1024;
; #pragma unroll
;                 for (int j = 0; j < 4; ++j) v[j] += *(const f32x4*)(pp + 256 * j + 4 * lane); }
;             float* wp = (float*)sp;
; #pragma unroll
;             for (int j = 0; j < 4; ++j) *(f32x4*)(wp + 256 * j + 4 * lane) = v[j];
;         }
.LBB0_533:
	v_add_u32_e32 v36, 0xffff8000, v18
	v_cmp_lt_i32_e32 vcc, s57, v18
	v_mov_b32_e32 v1, s7
	v_mov_b32_e32 v4, s1
	v_cndmask_b32_e64 v3, v19, 0, vcc
	v_cndmask_b32_e32 v2, v18, v36, vcc
	v_cndmask_b32_e32 v5, v1, v4, vcc
	v_mov_b32_e32 v1, s6
	v_mov_b32_e32 v4, s0
	v_cndmask_b32_e32 v4, v1, v4, vcc
	v_lshlrev_b64 v[2:3], 12, v[2:3]
	v_lshl_add_u64 v[2:3], v[4:5], 0, v[2:3]
	v_mov_b32_e32 v27, v0
	v_lshl_add_u64 v[34:35], v[2:3], 0, v[26:27]
	global_load_dwordx4 v[10:13], v[34:35], off
	global_load_dwordx4 v[6:9], v[34:35], off offset:1024
	global_load_dwordx4 v[2:5], v[34:35], off offset:2048
	global_load_dwordx4 v[14:17], v[34:35], off offset:3072
	v_mov_b32_e32 v37, v0
	s_and_saveexec_b64 s[2:3], vcc
	s_cbranch_execz .LBB0_532
	v_lshlrev_b64 v[36:37], 12, v[36:37]
	v_lshl_add_u64 v[36:37], v[20:21], 0, v[36:37]
	global_load_dwordx4 v[60:63], v[36:37], off
	global_load_dwordx4 v[64:67], v[36:37], off offset:1024
	global_load_dwordx4 v[68:71], v[36:37], off offset:2048
	global_load_dwordx4 v[72:75], v[36:37], off offset:3072
	s_mov_b32 s16, 0x400000
	v_add_co_u32_e32 v42, vcc, s16, v36
	s_nop 1
	v_addc_co_u32_e32 v43, vcc, 0, v37, vcc
	global_load_dwordx4 v[76:79], v[42:43], off
	global_load_dwordx4 v[80:83], v[42:43], off offset:1024
	global_load_dwordx4 v[84:87], v[42:43], off offset:2048
	global_load_dwordx4 v[88:91], v[42:43], off offset:3072
	s_mov_b32 s16, 0x800000
	v_add_co_u32_e32 v42, vcc, s16, v36
	s_nop 1
	v_addc_co_u32_e32 v43, vcc, 0, v37, vcc
	global_load_dwordx4 v[92:95], v[42:43], off
	global_load_dwordx4 v[96:99], v[42:43], off offset:1024
	global_load_dwordx4 v[100:103], v[42:43], off offset:2048
	global_load_dwordx4 v[104:107], v[42:43], off offset:3072
	s_mov_b32 s16, 0xc00000
	v_add_co_u32_e32 v42, vcc, s16, v36
	s_nop 1
	v_addc_co_u32_e32 v43, vcc, 0, v37, vcc
	global_load_dwordx4 v[108:111], v[42:43], off
	global_load_dwordx4 v[112:115], v[42:43], off offset:1024
	global_load_dwordx4 v[116:119], v[42:43], off offset:2048
	global_load_dwordx4 v[120:123], v[42:43], off offset:3072
	s_mov_b32 s16, 0x1000000
	v_add_co_u32_e32 v42, vcc, s16, v36
	s_nop 1
	v_addc_co_u32_e32 v43, vcc, 0, v37, vcc
	global_load_dwordx4 v[124:127], v[42:43], off
	global_load_dwordx4 v[128:131], v[42:43], off offset:1024
	global_load_dwordx4 v[132:135], v[42:43], off offset:2048
	global_load_dwordx4 v[136:139], v[42:43], off offset:3072
	s_mov_b32 s16, 0x1400000
	v_add_co_u32_e32 v42, vcc, s16, v36
	s_nop 1
	v_addc_co_u32_e32 v43, vcc, 0, v37, vcc
	global_load_dwordx4 v[140:143], v[42:43], off
	global_load_dwordx4 v[144:147], v[42:43], off offset:1024
	global_load_dwordx4 v[148:151], v[42:43], off offset:2048
	global_load_dwordx4 v[152:155], v[42:43], off offset:3072
	s_mov_b32 s16, 0x1800000
	v_add_co_u32_e32 v42, vcc, s16, v36
	s_nop 1
	v_addc_co_u32_e32 v43, vcc, 0, v37, vcc
	global_load_dwordx4 v[156:159], v[42:43], off
	global_load_dwordx4 v[160:163], v[42:43], off offset:1024
	global_load_dwordx4 v[164:167], v[42:43], off offset:2048
	global_load_dwordx4 v[168:171], v[42:43], off offset:3072
	s_mov_b32 s16, 0x1c00000
	v_add_co_u32_e32 v42, vcc, s16, v36
	s_nop 1
	v_addc_co_u32_e32 v43, vcc, 0, v37, vcc
	global_load_dwordx4 v[172:175], v[42:43], off
	global_load_dwordx4 v[176:179], v[42:43], off offset:1024
	global_load_dwordx4 v[180:183], v[42:43], off offset:2048
	global_load_dwordx4 v[184:187], v[42:43], off offset:3072
	s_waitcnt vmcnt(31)
	v_pk_add_f32 v[10:11], v[10:11], v[60:61]
	v_pk_add_f32 v[12:13], v[12:13], v[62:63]
	s_waitcnt vmcnt(30)
	v_pk_add_f32 v[6:7], v[6:7], v[64:65]
	v_pk_add_f32 v[8:9], v[8:9], v[66:67]
	s_waitcnt vmcnt(29)
	v_pk_add_f32 v[2:3], v[2:3], v[68:69]
	v_pk_add_f32 v[4:5], v[4:5], v[70:71]
	s_waitcnt vmcnt(28)
	v_pk_add_f32 v[14:15], v[14:15], v[72:73]
	v_pk_add_f32 v[16:17], v[16:17], v[74:75]
	s_mov_b32 s16, 0x2000000
	v_add_co_u32_e32 v42, vcc, s16, v36
	s_nop 1
	v_addc_co_u32_e32 v43, vcc, 0, v37, vcc
	global_load_dwordx4 v[60:63], v[42:43], off
	global_load_dwordx4 v[64:67], v[42:43], off offset:1024
	global_load_dwordx4 v[68:71], v[42:43], off offset:2048
	global_load_dwordx4 v[72:75], v[42:43], off offset:3072
	s_waitcnt vmcnt(31)
	v_pk_add_f32 v[10:11], v[10:11], v[76:77]
	v_pk_add_f32 v[12:13], v[12:13], v[78:79]
	s_waitcnt vmcnt(30)
	v_pk_add_f32 v[6:7], v[6:7], v[80:81]
	v_pk_add_f32 v[8:9], v[8:9], v[82:83]
	s_waitcnt vmcnt(29)
	v_pk_add_f32 v[2:3], v[2:3], v[84:85]
	v_pk_add_f32 v[4:5], v[4:5], v[86:87]
	s_waitcnt vmcnt(28)
; __device__ void norm_mod_phase(const float* srcL, const float* srcC, float* cpyL, float* cpyC, const float* g, const float* mod, bf16_t* TN, int nrows, const float* pb, int nsl) {
;     ...
;         if (!lat && nsl > 0) {
;             for (int sl = 0; sl < nsl; ++sl) { const float* pp = pb + ((size_t)sl * 1024 + (row - RL)) * 1024;
; #pragma unroll
;                 for (int j = 0; j < 4; ++j) v[j] += *(const f32x4*)(pp + 256 * j + 4 * lane); }
;             float* wp = (float*)sp;
; #pragma unroll
;             for (int j = 0; j < 4; ++j) *(f32x4*)(wp + 256 * j + 4 * lane) = v[j];
;         }
	v_pk_add_f32 v[14:15], v[14:15], v[88:89]
	v_pk_add_f32 v[16:17], v[16:17], v[90:91]
	s_mov_b32 s16, 0x2400000
	v_add_co_u32_e32 v42, vcc, s16, v36
	s_nop 1
	v_addc_co_u32_e32 v43, vcc, 0, v37, vcc
	global_load_dwordx4 v[76:79], v[42:43], off
	global_load_dwordx4 v[80:83], v[42:43], off offset:1024
	global_load_dwordx4 v[84:87], v[42:43], off offset:2048
	global_load_dwordx4 v[88:91], v[42:43], off offset:3072
	s_waitcnt vmcnt(31)
	v_pk_add_f32 v[10:11], v[10:11], v[92:93]
	v_pk_add_f32 v[12:13], v[12:13], v[94:95]
	s_waitcnt vmcnt(30)
	v_pk_add_f32 v[6:7], v[6:7], v[96:97]
	v_pk_add_f32 v[8:9], v[8:9], v[98:99]
	s_waitcnt vmcnt(29)
	v_pk_add_f32 v[2:3], v[2:3], v[100:101]
	v_pk_add_f32 v[4:5], v[4:5], v[102:103]
	s_waitcnt vmcnt(28)
	v_pk_add_f32 v[14:15], v[14:15], v[104:105]
	v_pk_add_f32 v[16:17], v[16:17], v[106:107]
	s_mov_b32 s16, 0x2800000
	v_add_co_u32_e32 v42, vcc, s16, v36
	s_nop 1
	v_addc_co_u32_e32 v43, vcc, 0, v37, vcc
	global_load_dwordx4 v[92:95], v[42:43], off
	global_load_dwordx4 v[96:99], v[42:43], off offset:1024
	global_load_dwordx4 v[100:103], v[42:43], off offset:2048
	global_load_dwordx4 v[104:107], v[42:43], off offset:3072
	s_waitcnt vmcnt(31)
	v_pk_add_f32 v[10:11], v[10:11], v[108:109]
	v_pk_add_f32 v[12:13], v[12:13], v[110:111]
	s_waitcnt vmcnt(30)
	v_pk_add_f32 v[6:7], v[6:7], v[112:113]
	v_pk_add_f32 v[8:9], v[8:9], v[114:115]
	s_waitcnt vmcnt(29)
	v_pk_add_f32 v[2:3], v[2:3], v[116:117]
	v_pk_add_f32 v[4:5], v[4:5], v[118:119]
	s_waitcnt vmcnt(28)
	v_pk_add_f32 v[14:15], v[14:15], v[120:121]
	v_pk_add_f32 v[16:17], v[16:17], v[122:123]
	s_waitcnt vmcnt(27)
	v_pk_add_f32 v[10:11], v[10:11], v[124:125]
	v_pk_add_f32 v[12:13], v[12:13], v[126:127]
	s_waitcnt vmcnt(26)
	v_pk_add_f32 v[6:7], v[6:7], v[128:129]
	v_pk_add_f32 v[8:9], v[8:9], v[130:131]
	s_waitcnt vmcnt(25)
	v_pk_add_f32 v[2:3], v[2:3], v[132:133]
	v_pk_add_f32 v[4:5], v[4:5], v[134:135]
	s_waitcnt vmcnt(24)
	v_pk_add_f32 v[14:15], v[14:15], v[136:137]
	v_pk_add_f32 v[16:17], v[16:17], v[138:139]
	s_waitcnt vmcnt(23)
	v_pk_add_f32 v[10:11], v[10:11], v[140:141]
	v_pk_add_f32 v[12:13], v[12:13], v[142:143]
	s_waitcnt vmcnt(22)
	v_pk_add_f32 v[6:7], v[6:7], v[144:145]
	v_pk_add_f32 v[8:9], v[8:9], v[146:147]
	s_waitcnt vmcnt(21)
	v_pk_add_f32 v[2:3], v[2:3], v[148:149]
	v_pk_add_f32 v[4:5], v[4:5], v[150:151]
	s_waitcnt vmcnt(20)
	v_pk_add_f32 v[14:15], v[14:15], v[152:153]
	v_pk_add_f32 v[16:17], v[16:17], v[154:155]
	s_waitcnt vmcnt(19)
	v_pk_add_f32 v[10:11], v[10:11], v[156:157]
	v_pk_add_f32 v[12:13], v[12:13], v[158:159]
	s_waitcnt vmcnt(18)
	v_pk_add_f32 v[6:7], v[6:7], v[160:161]
	v_pk_add_f32 v[8:9], v[8:9], v[162:163]
	s_waitcnt vmcnt(17)
	v_pk_add_f32 v[2:3], v[2:3], v[164:165]
	v_pk_add_f32 v[4:5], v[4:5], v[166:167]
	s_waitcnt vmcnt(16)
	v_pk_add_f32 v[14:15], v[14:15], v[168:169]
	v_pk_add_f32 v[16:17], v[16:17], v[170:171]
	s_waitcnt vmcnt(15)
	v_pk_add_f32 v[10:11], v[10:11], v[172:173]
	v_pk_add_f32 v[12:13], v[12:13], v[174:175]
	s_waitcnt vmcnt(14)
	v_pk_add_f32 v[6:7], v[6:7], v[176:177]
	v_pk_add_f32 v[8:9], v[8:9], v[178:179]
	s_waitcnt vmcnt(13)
	v_pk_add_f32 v[2:3], v[2:3], v[180:181]
	v_pk_add_f32 v[4:5], v[4:5], v[182:183]
	s_waitcnt vmcnt(12)
	v_pk_add_f32 v[14:15], v[14:15], v[184:185]
	v_pk_add_f32 v[16:17], v[16:17], v[186:187]
	s_waitcnt vmcnt(11)
	v_pk_add_f32 v[10:11], v[10:11], v[60:61]
	v_pk_add_f32 v[12:13], v[12:13], v[62:63]
	s_waitcnt vmcnt(10)
	v_pk_add_f32 v[6:7], v[6:7], v[64:65]
	v_pk_add_f32 v[8:9], v[8:9], v[66:67]
	s_waitcnt vmcnt(9)
	v_pk_add_f32 v[2:3], v[2:3], v[68:69]
	v_pk_add_f32 v[4:5], v[4:5], v[70:71]
	s_waitcnt vmcnt(8)
	v_pk_add_f32 v[14:15], v[14:15], v[72:73]
	v_pk_add_f32 v[16:17], v[16:17], v[74:75]
	s_waitcnt vmcnt(7)
	v_pk_add_f32 v[10:11], v[10:11], v[76:77]
	v_pk_add_f32 v[12:13], v[12:13], v[78:79]
	s_waitcnt vmcnt(6)
	v_pk_add_f32 v[6:7], v[6:7], v[80:81]
	v_pk_add_f32 v[8:9], v[8:9], v[82:83]
	s_waitcnt vmcnt(5)
	v_pk_add_f32 v[2:3], v[2:3], v[84:85]
	v_pk_add_f32 v[4:5], v[4:5], v[86:87]
	s_waitcnt vmcnt(4)
	v_pk_add_f32 v[14:15], v[14:15], v[88:89]
	v_pk_add_f32 v[16:17], v[16:17], v[90:91]
	s_waitcnt vmcnt(3)
	v_pk_add_f32 v[10:11], v[10:11], v[92:93]
	v_pk_add_f32 v[12:13], v[12:13], v[94:95]
	s_waitcnt vmcnt(2)
	v_pk_add_f32 v[6:7], v[6:7], v[96:97]
	v_pk_add_f32 v[8:9], v[8:9], v[98:99]
	s_waitcnt vmcnt(1)
	v_pk_add_f32 v[2:3], v[2:3], v[100:101]
	v_pk_add_f32 v[4:5], v[4:5], v[102:103]
	s_waitcnt vmcnt(0)
	v_pk_add_f32 v[14:15], v[14:15], v[104:105]
	v_pk_add_f32 v[16:17], v[16:17], v[106:107]
	global_store_dwordx4 v[34:35], v[10:13], off
	global_store_dwordx4 v[34:35], v[6:9], off offset:1024
	global_store_dwordx4 v[34:35], v[2:5], off offset:2048
	global_store_dwordx4 v[34:35], v[14:17], off offset:3072
	s_branch .LBB0_532

; __device__ void norm_mod_phase(const float* srcL, const float* srcC, float* cpyL, float* cpyC, const float* g, const float* mod, bf16_t* TN, int nrows, const float* pb, int nsl) {
;     ...
;         const float* sp = lat ? srcL + (size_t)row * 1024 : srcC + (size_t)(row - RL) * 1024;
;         const float* mp = mod + (lat ? (row >> 13) : 4) * 9216;
;         f32x4 v[4]; float ss = 0.f;
; #pragma unroll
;         for (int j = 0; j < 4; ++j) v[j] = *(const f32x4*)(sp + 256 * j + 4 * lane);
;         if (!lat && nsl > 0) {
;             for (int sl = 0; sl < nsl; ++sl) { const float* pp = pb + ((size_t)sl * 1024 + (row - RL)) * 1024;
; #pragma unroll
;                 for (int j = 0; j < 4; ++j) v[j] += *(const f32x4*)(pp + 256 * j + 4 * lane); }
;             float* wp = (float*)sp;
; #pragma unroll
;             for (int j = 0; j < 4; ++j) *(f32x4*)(wp + 256 * j + 4 * lane) = v[j];
;         }
.LBB0_635:
	v_add_u32_e32 v36, 0xffff8000, v18
	v_cmp_lt_i32_e32 vcc, s57, v18
	v_mov_b32_e32 v1, s9
	v_mov_b32_e32 v4, s1
	v_cndmask_b32_e64 v3, v19, 0, vcc
	v_cndmask_b32_e32 v2, v18, v36, vcc
	v_cndmask_b32_e32 v5, v1, v4, vcc
	v_mov_b32_e32 v1, s8
	v_mov_b32_e32 v4, s0
	v_cndmask_b32_e32 v4, v1, v4, vcc
	v_lshlrev_b64 v[2:3], 12, v[2:3]
	v_lshl_add_u64 v[2:3], v[4:5], 0, v[2:3]
	v_mov_b32_e32 v27, v0
	v_lshl_add_u64 v[34:35], v[2:3], 0, v[26:27]
	global_load_dwordx4 v[10:13], v[34:35], off
	global_load_dwordx4 v[6:9], v[34:35], off offset:1024
	global_load_dwordx4 v[2:5], v[34:35], off offset:2048
	global_load_dwordx4 v[14:17], v[34:35], off offset:3072
	v_mov_b32_e32 v37, v0
	s_and_saveexec_b64 s[2:3], vcc
	s_cbranch_execz .LBB0_634
	v_lshlrev_b64 v[36:37], 12, v[36:37]
	v_lshl_add_u64 v[36:37], v[20:21], 0, v[36:37]
	global_load_dwordx4 v[60:63], v[36:37], off
	global_load_dwordx4 v[64:67], v[36:37], off offset:1024
	global_load_dwordx4 v[68:71], v[36:37], off offset:2048
	global_load_dwordx4 v[72:75], v[36:37], off offset:3072
	s_mov_b32 s18, 0x400000
	v_add_co_u32_e32 v42, vcc, s18, v36
	s_nop 1
	v_addc_co_u32_e32 v43, vcc, 0, v37, vcc
	global_load_dwordx4 v[76:79], v[42:43], off
	global_load_dwordx4 v[80:83], v[42:43], off offset:1024
	global_load_dwordx4 v[84:87], v[42:43], off offset:2048
	global_load_dwordx4 v[88:91], v[42:43], off offset:3072
	s_mov_b32 s18, 0x800000
	v_add_co_u32_e32 v42, vcc, s18, v36
	s_nop 1
	v_addc_co_u32_e32 v43, vcc, 0, v37, vcc
	global_load_dwordx4 v[92:95], v[42:43], off
	global_load_dwordx4 v[96:99], v[42:43], off offset:1024
	global_load_dwordx4 v[100:103], v[42:43], off offset:2048
	global_load_dwordx4 v[104:107], v[42:43], off offset:3072
	s_mov_b32 s18, 0xc00000
	v_add_co_u32_e32 v42, vcc, s18, v36
	s_nop 1
	v_addc_co_u32_e32 v43, vcc, 0, v37, vcc
	global_load_dwordx4 v[108:111], v[42:43], off
	global_load_dwordx4 v[112:115], v[42:43], off offset:1024
	global_load_dwordx4 v[116:119], v[42:43], off offset:2048
	global_load_dwordx4 v[120:123], v[42:43], off offset:3072
	s_mov_b32 s18, 0x1000000
	v_add_co_u32_e32 v42, vcc, s18, v36
	s_nop 1
	v_addc_co_u32_e32 v43, vcc, 0, v37, vcc
	global_load_dwordx4 v[124:127], v[42:43], off
	global_load_dwordx4 v[128:131], v[42:43], off offset:1024
	global_load_dwordx4 v[132:135], v[42:43], off offset:2048
	global_load_dwordx4 v[136:139], v[42:43], off offset:3072
	s_mov_b32 s18, 0x1400000
	v_add_co_u32_e32 v42, vcc, s18, v36
	s_nop 1
	v_addc_co_u32_e32 v43, vcc, 0, v37, vcc
	global_load_dwordx4 v[140:143], v[42:43], off
	global_load_dwordx4 v[144:147], v[42:43], off offset:1024
	global_load_dwordx4 v[148:151], v[42:43], off offset:2048
	global_load_dwordx4 v[152:155], v[42:43], off offset:3072
	s_mov_b32 s18, 0x1800000
	v_add_co_u32_e32 v42, vcc, s18, v36
	s_nop 1
	v_addc_co_u32_e32 v43, vcc, 0, v37, vcc
	global_load_dwordx4 v[156:159], v[42:43], off
	global_load_dwordx4 v[160:163], v[42:43], off offset:1024
	global_load_dwordx4 v[164:167], v[42:43], off offset:2048
	global_load_dwordx4 v[168:171], v[42:43], off offset:3072
	s_mov_b32 s18, 0x1c00000
	v_add_co_u32_e32 v42, vcc, s18, v36
	s_nop 1
	v_addc_co_u32_e32 v43, vcc, 0, v37, vcc
	global_load_dwordx4 v[172:175], v[42:43], off
	global_load_dwordx4 v[176:179], v[42:43], off offset:1024
	global_load_dwordx4 v[180:183], v[42:43], off offset:2048
	global_load_dwordx4 v[184:187], v[42:43], off offset:3072
	s_waitcnt vmcnt(31)
	v_pk_add_f32 v[10:11], v[10:11], v[60:61]
	v_pk_add_f32 v[12:13], v[12:13], v[62:63]
	s_waitcnt vmcnt(30)
	v_pk_add_f32 v[6:7], v[6:7], v[64:65]
	v_pk_add_f32 v[8:9], v[8:9], v[66:67]
	s_waitcnt vmcnt(29)
	v_pk_add_f32 v[2:3], v[2:3], v[68:69]
	v_pk_add_f32 v[4:5], v[4:5], v[70:71]
	s_waitcnt vmcnt(28)
	v_pk_add_f32 v[14:15], v[14:15], v[72:73]
	v_pk_add_f32 v[16:17], v[16:17], v[74:75]
	s_mov_b32 s18, 0x2000000
	v_add_co_u32_e32 v42, vcc, s18, v36
	s_nop 1
	v_addc_co_u32_e32 v43, vcc, 0, v37, vcc
	global_load_dwordx4 v[60:63], v[42:43], off
	global_load_dwordx4 v[64:67], v[42:43], off offset:1024
	global_load_dwordx4 v[68:71], v[42:43], off offset:2048
	global_load_dwordx4 v[72:75], v[42:43], off offset:3072
	s_waitcnt vmcnt(31)
	v_pk_add_f32 v[10:11], v[10:11], v[76:77]
	v_pk_add_f32 v[12:13], v[12:13], v[78:79]
	s_waitcnt vmcnt(30)
	v_pk_add_f32 v[6:7], v[6:7], v[80:81]
	v_pk_add_f32 v[8:9], v[8:9], v[82:83]
	s_waitcnt vmcnt(29)
	v_pk_add_f32 v[2:3], v[2:3], v[84:85]
	v_pk_add_f32 v[4:5], v[4:5], v[86:87]
	s_waitcnt vmcnt(28)
; __device__ void norm_mod_phase(const float* srcL, const float* srcC, float* cpyL, float* cpyC, const float* g, const float* mod, bf16_t* TN, int nrows, const float* pb, int nsl) {
;     ...
;         if (!lat && nsl > 0) {
;             for (int sl = 0; sl < nsl; ++sl) { const float* pp = pb + ((size_t)sl * 1024 + (row - RL)) * 1024;
; #pragma unroll
;                 for (int j = 0; j < 4; ++j) v[j] += *(const f32x4*)(pp + 256 * j + 4 * lane); }
;             float* wp = (float*)sp;
; #pragma unroll
;             for (int j = 0; j < 4; ++j) *(f32x4*)(wp + 256 * j + 4 * lane) = v[j];
;         }
	v_pk_add_f32 v[14:15], v[14:15], v[88:89]
	v_pk_add_f32 v[16:17], v[16:17], v[90:91]
	s_mov_b32 s18, 0x2400000
	v_add_co_u32_e32 v42, vcc, s18, v36
	s_nop 1
	v_addc_co_u32_e32 v43, vcc, 0, v37, vcc
	global_load_dwordx4 v[76:79], v[42:43], off
	global_load_dwordx4 v[80:83], v[42:43], off offset:1024
	global_load_dwordx4 v[84:87], v[42:43], off offset:2048
	global_load_dwordx4 v[88:91], v[42:43], off offset:3072
	s_waitcnt vmcnt(31)
	v_pk_add_f32 v[10:11], v[10:11], v[92:93]
	v_pk_add_f32 v[12:13], v[12:13], v[94:95]
	s_waitcnt vmcnt(30)
	v_pk_add_f32 v[6:7], v[6:7], v[96:97]
	v_pk_add_f32 v[8:9], v[8:9], v[98:99]
	s_waitcnt vmcnt(29)
	v_pk_add_f32 v[2:3], v[2:3], v[100:101]
	v_pk_add_f32 v[4:5], v[4:5], v[102:103]
	s_waitcnt vmcnt(28)
	v_pk_add_f32 v[14:15], v[14:15], v[104:105]
	v_pk_add_f32 v[16:17], v[16:17], v[106:107]
	s_mov_b32 s18, 0x2800000
	v_add_co_u32_e32 v42, vcc, s18, v36
	s_nop 1
	v_addc_co_u32_e32 v43, vcc, 0, v37, vcc
	global_load_dwordx4 v[92:95], v[42:43], off
	global_load_dwordx4 v[96:99], v[42:43], off offset:1024
	global_load_dwordx4 v[100:103], v[42:43], off offset:2048
	global_load_dwordx4 v[104:107], v[42:43], off offset:3072
	s_waitcnt vmcnt(31)
	v_pk_add_f32 v[10:11], v[10:11], v[108:109]
	v_pk_add_f32 v[12:13], v[12:13], v[110:111]
	s_waitcnt vmcnt(30)
	v_pk_add_f32 v[6:7], v[6:7], v[112:113]
	v_pk_add_f32 v[8:9], v[8:9], v[114:115]
	s_waitcnt vmcnt(29)
	v_pk_add_f32 v[2:3], v[2:3], v[116:117]
	v_pk_add_f32 v[4:5], v[4:5], v[118:119]
	s_waitcnt vmcnt(28)
	v_pk_add_f32 v[14:15], v[14:15], v[120:121]
	v_pk_add_f32 v[16:17], v[16:17], v[122:123]
	s_waitcnt vmcnt(27)
	v_pk_add_f32 v[10:11], v[10:11], v[124:125]
	v_pk_add_f32 v[12:13], v[12:13], v[126:127]
	s_waitcnt vmcnt(26)
	v_pk_add_f32 v[6:7], v[6:7], v[128:129]
	v_pk_add_f32 v[8:9], v[8:9], v[130:131]
	s_waitcnt vmcnt(25)
	v_pk_add_f32 v[2:3], v[2:3], v[132:133]
	v_pk_add_f32 v[4:5], v[4:5], v[134:135]
	s_waitcnt vmcnt(24)
	v_pk_add_f32 v[14:15], v[14:15], v[136:137]
	v_pk_add_f32 v[16:17], v[16:17], v[138:139]
	s_waitcnt vmcnt(23)
	v_pk_add_f32 v[10:11], v[10:11], v[140:141]
	v_pk_add_f32 v[12:13], v[12:13], v[142:143]
	s_waitcnt vmcnt(22)
	v_pk_add_f32 v[6:7], v[6:7], v[144:145]
	v_pk_add_f32 v[8:9], v[8:9], v[146:147]
	s_waitcnt vmcnt(21)
	v_pk_add_f32 v[2:3], v[2:3], v[148:149]
	v_pk_add_f32 v[4:5], v[4:5], v[150:151]
	s_waitcnt vmcnt(20)
	v_pk_add_f32 v[14:15], v[14:15], v[152:153]
	v_pk_add_f32 v[16:17], v[16:17], v[154:155]
	s_waitcnt vmcnt(19)
	v_pk_add_f32 v[10:11], v[10:11], v[156:157]
	v_pk_add_f32 v[12:13], v[12:13], v[158:159]
	s_waitcnt vmcnt(18)
	v_pk_add_f32 v[6:7], v[6:7], v[160:161]
	v_pk_add_f32 v[8:9], v[8:9], v[162:163]
	s_waitcnt vmcnt(17)
	v_pk_add_f32 v[2:3], v[2:3], v[164:165]
	v_pk_add_f32 v[4:5], v[4:5], v[166:167]
	s_waitcnt vmcnt(16)
	v_pk_add_f32 v[14:15], v[14:15], v[168:169]
	v_pk_add_f32 v[16:17], v[16:17], v[170:171]
	s_waitcnt vmcnt(15)
	v_pk_add_f32 v[10:11], v[10:11], v[172:173]
	v_pk_add_f32 v[12:13], v[12:13], v[174:175]
	s_waitcnt vmcnt(14)
	v_pk_add_f32 v[6:7], v[6:7], v[176:177]
	v_pk_add_f32 v[8:9], v[8:9], v[178:179]
	s_waitcnt vmcnt(13)
	v_pk_add_f32 v[2:3], v[2:3], v[180:181]
	v_pk_add_f32 v[4:5], v[4:5], v[182:183]
	s_waitcnt vmcnt(12)
	v_pk_add_f32 v[14:15], v[14:15], v[184:185]
	v_pk_add_f32 v[16:17], v[16:17], v[186:187]
	s_waitcnt vmcnt(11)
	v_pk_add_f32 v[10:11], v[10:11], v[60:61]
	v_pk_add_f32 v[12:13], v[12:13], v[62:63]
	s_waitcnt vmcnt(10)
	v_pk_add_f32 v[6:7], v[6:7], v[64:65]
	v_pk_add_f32 v[8:9], v[8:9], v[66:67]
	s_waitcnt vmcnt(9)
	v_pk_add_f32 v[2:3], v[2:3], v[68:69]
	v_pk_add_f32 v[4:5], v[4:5], v[70:71]
	s_waitcnt vmcnt(8)
	v_pk_add_f32 v[14:15], v[14:15], v[72:73]
	v_pk_add_f32 v[16:17], v[16:17], v[74:75]
	s_waitcnt vmcnt(7)
	v_pk_add_f32 v[10:11], v[10:11], v[76:77]
	v_pk_add_f32 v[12:13], v[12:13], v[78:79]
	s_waitcnt vmcnt(6)
	v_pk_add_f32 v[6:7], v[6:7], v[80:81]
	v_pk_add_f32 v[8:9], v[8:9], v[82:83]
	s_waitcnt vmcnt(5)
	v_pk_add_f32 v[2:3], v[2:3], v[84:85]
	v_pk_add_f32 v[4:5], v[4:5], v[86:87]
	s_waitcnt vmcnt(4)
	v_pk_add_f32 v[14:15], v[14:15], v[88:89]
	v_pk_add_f32 v[16:17], v[16:17], v[90:91]
	s_waitcnt vmcnt(3)
	v_pk_add_f32 v[10:11], v[10:11], v[92:93]
	v_pk_add_f32 v[12:13], v[12:13], v[94:95]
	s_waitcnt vmcnt(2)
	v_pk_add_f32 v[6:7], v[6:7], v[96:97]
	v_pk_add_f32 v[8:9], v[8:9], v[98:99]
	s_waitcnt vmcnt(1)
	v_pk_add_f32 v[2:3], v[2:3], v[100:101]
	v_pk_add_f32 v[4:5], v[4:5], v[102:103]
	s_waitcnt vmcnt(0)
	v_pk_add_f32 v[14:15], v[14:15], v[104:105]
	v_pk_add_f32 v[16:17], v[16:17], v[106:107]
	global_store_dwordx4 v[34:35], v[10:13], off
	global_store_dwordx4 v[34:35], v[6:9], off offset:1024
	global_store_dwordx4 v[34:35], v[2:5], off offset:2048
	global_store_dwordx4 v[34:35], v[14:17], off offset:3072
	s_branch .LBB0_634
